# hyena: epilogue x0c/bias loads issued before the lag loop
# speedup vs baseline: 1.0099x; 1.0022x over previous
; #define LAS __attribute__((address_space(3)))
; DI unsigned cvt_pk_bf16(float lo, float hi) { const f32x2 v = {lo, hi}; return __builtin_bit_cast(unsigned, __builtin_convertvector(v, bf16x2_t)); }
; DI float bflo(unsigned w) { return __uint_as_float(w << 16); }
; DI float bfhi(unsigned w) { return __uint_as_float(w & 0xffff0000u); }
; DI void hyena_unit(const Inputs& in, int l, unsigned char* ws, int half, int c, LAS unsigned char* lds, int tid) {
;     ...
;     const float bias = in.hy_bias[l * 512 + c];
;     u32x2 xx[2][4];
; #pragma unroll
;     for (int k = 0; k < 2; ++k)
; #pragma unroll
;         for (int q = 0; q < 4; ++q) xx[k][q] = *(const u32x2*)(XT + (size_t)((b0 + k) * 512 + c) * L + 32 * (a0 + i32) + 8 * q + 4 * g);
; #pragma unroll
;     for (int k = 0; k < 2; ++k) {
;         const int a = a0 + i32, b = b0 + k;
; #pragma unroll
;         for (int q = 0; q < 4; ++q) {
;             const int t0 = 32 * a + 8 * q + 4 * g;
;             const u32x2 zz = *(const LAS u32x2*)(Zb + k * zstep + ((32 + a) * 40 + 8 * q + 4 * g) * 2);
;             bf16_t* xp = XT + (size_t)(b * 512 + c) * L + t0;
;             const float z0 = bflo(zz.x), z1 = bfhi(zz.x), z2 = bflo(zz.y), z3 = bfhi(zz.y);
;             const float x0 = bflo(xx[k][q].x), x1 = bfhi(xx[k][q].x), x2 = bflo(xx[k][q].y), x3 = bfhi(xx[k][q].y);
;             const float c0 = k ? acc1[4 * q + 0] : acc0[4 * q + 0], c1 = k ? acc1[4 * q + 1] : acc0[4 * q + 1], c2 = k ? acc1[4 * q + 2] : acc0[4 * q + 2], c3 = k ? acc1[4 * q + 3] : acc0[4 * q + 3];
;             u32x2 o; o.x = cvt_pk_bf16((c0 + z0 * bias) * x0, (c1 + z1 * bias) * x1); o.y = cvt_pk_bf16((c2 + z2 * bias) * x2, (c3 + z3 * bias) * x3);
;             *(u32x2*)xp = o;
;         }
;     }
.LBB0_617:
	s_or_b64 exec, exec, vcc
	s_waitcnt vmcnt(0)
	v_readlane_b32 s42, v255, 13
	s_add_i32 s74, s79, s42
	s_ashr_i32 s75, s74, 31
	s_lshl_b64 s[74:75], s[74:75], 2
	s_add_u32 s74, s60, s74
	v_add_u32_e32 v34, s79, v92
	s_addc_u32 s75, s61, s75
	v_ashrrev_i32_e32 v35, 31, v34
	v_mov_b32_e32 v32, v200
	v_lshlrev_b64 v[34:35], s33, v[34:35]
	v_lshlrev_b64 v[44:45], 1, v[34:35]
	v_lshl_add_u64 v[34:35], v[86:87], 0, v[44:45]
	v_mov_b32_e32 v120, v184
	v_mov_b32_e32 v121, v185
	v_mov_b32_e32 v122, v186
	v_mov_b32_e32 v123, v187
	v_mov_b32_e32 v124, v188
	v_mov_b32_e32 v125, v189
	v_mov_b32_e32 v126, v190
	v_mov_b32_e32 v127, v191
	v_add_u32_e32 v34, s79, v93
	v_ashrrev_i32_e32 v35, 31, v34
	v_lshlrev_b64 v[34:35], s33, v[34:35]
	v_lshlrev_b64 v[42:43], 1, v[34:35]
	v_lshl_add_u64 v[34:35], v[86:87], 0, v[42:43]
	v_mov_b32_e32 v40, v192
	v_mov_b32_e32 v41, v193
	v_mov_b32_e32 v38, v194
	v_mov_b32_e32 v39, v195
	v_mov_b32_e32 v36, v196
	v_mov_b32_e32 v37, v197
	s_nop 0
	v_mov_b32_e32 v34, v198
	v_mov_b32_e32 v35, v199
	v_add_u32_e32 v33, v90, v94
	v_add_u32_e32 v33, 0x8080, v33
	v_lshl_add_u64 v[128:129], v[88:89], 0, v[44:45]
	ds_read2_b64 v[44:47], v33 offset0:64 offset1:66
	ds_read2_b64 v[48:51], v33 offset0:68 offset1:70
	s_add_i32 s79, s79, s71
	s_cmpk_lt_i32 s79, 0x200
	s_waitcnt lgkmcnt(1)
	v_lshlrev_b32_e32 v130, 16, v44
	v_and_b32_e32 v131, 0xffff0000, v44
	v_lshlrev_b32_e32 v44, 16, v45
	v_and_b32_e32 v45, 0xffff0000, v45
	s_waitcnt vmcnt(8)
	v_pk_fma_f32 v[16:17], v[32:33], v[130:131], v[16:17] op_sel_hi:[0,1,1]
	s_waitcnt vmcnt(7)
	v_lshlrev_b32_e32 v132, 16, v120
	v_and_b32_e32 v133, 0xffff0000, v120
	v_lshlrev_b32_e32 v120, 16, v121
	v_and_b32_e32 v121, 0xffff0000, v121
	v_pk_fma_f32 v[18:19], v[32:33], v[44:45], v[18:19] op_sel_hi:[0,1,1]
	v_pk_mul_f32 v[16:17], v[16:17], v[132:133]
	v_pk_mul_f32 v[18:19], v[18:19], v[120:121]
	v_cvt_pk_bf16_f32 v16, v16, v17
	v_cvt_pk_bf16_f32 v17, v18, v19
	global_store_dwordx2 v[128:129], v[16:17], off
	v_lshlrev_b32_e32 v16, 16, v46
	v_and_b32_e32 v17, 0xffff0000, v46
	s_waitcnt vmcnt(7)
	v_lshlrev_b32_e32 v18, 16, v122
	v_and_b32_e32 v19, 0xffff0000, v122
	v_pk_fma_f32 v[16:17], v[32:33], v[16:17], v[20:21] op_sel_hi:[0,1,1]
	v_pk_mul_f32 v[16:17], v[16:17], v[18:19]
	v_lshlrev_b32_e32 v18, 16, v47
	v_and_b32_e32 v19, 0xffff0000, v47
	v_lshlrev_b32_e32 v20, 16, v123
	v_and_b32_e32 v21, 0xffff0000, v123
	v_pk_fma_f32 v[18:19], v[32:33], v[18:19], v[22:23] op_sel_hi:[0,1,1]
	v_pk_mul_f32 v[18:19], v[18:19], v[20:21]
	v_cvt_pk_bf16_f32 v16, v16, v17
	v_cvt_pk_bf16_f32 v17, v18, v19
	global_store_dwordx2 v[128:129], v[16:17], off offset:16
	s_waitcnt lgkmcnt(0)
	v_lshlrev_b32_e32 v16, 16, v48
	v_and_b32_e32 v17, 0xffff0000, v48
	s_waitcnt vmcnt(7)
	v_lshlrev_b32_e32 v18, 16, v124
	v_and_b32_e32 v19, 0xffff0000, v124
	v_pk_fma_f32 v[16:17], v[32:33], v[16:17], v[24:25] op_sel_hi:[0,1,1]
	v_pk_mul_f32 v[16:17], v[16:17], v[18:19]
	v_lshlrev_b32_e32 v18, 16, v49
	v_and_b32_e32 v19, 0xffff0000, v49
	v_lshlrev_b32_e32 v20, 16, v125
	v_and_b32_e32 v21, 0xffff0000, v125
	v_pk_fma_f32 v[18:19], v[32:33], v[18:19], v[26:27] op_sel_hi:[0,1,1]
	v_pk_mul_f32 v[18:19], v[18:19], v[20:21]
	v_cvt_pk_bf16_f32 v16, v16, v17
	v_cvt_pk_bf16_f32 v17, v18, v19
	global_store_dwordx2 v[128:129], v[16:17], off offset:32
	v_lshlrev_b32_e32 v16, 16, v50
	v_and_b32_e32 v17, 0xffff0000, v50
	s_waitcnt vmcnt(7)
	v_lshlrev_b32_e32 v18, 16, v126
	v_and_b32_e32 v19, 0xffff0000, v126
	v_pk_fma_f32 v[16:17], v[32:33], v[16:17], v[28:29] op_sel_hi:[0,1,1]
	v_pk_mul_f32 v[16:17], v[16:17], v[18:19]
	v_lshlrev_b32_e32 v18, 16, v51
	v_and_b32_e32 v19, 0xffff0000, v51
	v_lshlrev_b32_e32 v20, 16, v127
	v_and_b32_e32 v21, 0xffff0000, v127
	v_pk_fma_f32 v[18:19], v[32:33], v[18:19], v[30:31] op_sel_hi:[0,1,1]
	v_pk_mul_f32 v[18:19], v[18:19], v[20:21]
	v_cvt_pk_bf16_f32 v16, v16, v17
	v_cvt_pk_bf16_f32 v17, v18, v19
	v_add_u32_e32 v26, 0x8080, v119
	global_store_dwordx2 v[128:129], v[16:17], off offset:48
	ds_read2_b64 v[16:19], v26 offset0:64 offset1:66
	s_waitcnt vmcnt(7)
	v_lshlrev_b32_e32 v24, 16, v40
	v_and_b32_e32 v25, 0xffff0000, v40
	v_lshl_add_u64 v[20:21], v[88:89], 0, v[42:43]
	s_waitcnt lgkmcnt(0)
	v_lshlrev_b32_e32 v22, 16, v16
	v_and_b32_e32 v23, 0xffff0000, v16
	v_lshlrev_b32_e32 v16, 16, v17
	v_and_b32_e32 v17, 0xffff0000, v17
	v_pk_fma_f32 v[0:1], v[32:33], v[22:23], v[0:1] op_sel_hi:[0,1,1]
	v_lshlrev_b32_e32 v22, 16, v41
	v_and_b32_e32 v23, 0xffff0000, v41
	v_pk_fma_f32 v[2:3], v[32:33], v[16:17], v[2:3] op_sel_hi:[0,1,1]
	v_pk_mul_f32 v[0:1], v[0:1], v[24:25]
	v_pk_mul_f32 v[2:3], v[2:3], v[22:23]
	v_cvt_pk_bf16_f32 v0, v0, v1
	v_cvt_pk_bf16_f32 v1, v2, v3
	global_store_dwordx2 v[20:21], v[0:1], off
	v_lshlrev_b32_e32 v0, 16, v18
	v_and_b32_e32 v1, 0xffff0000, v18
	s_waitcnt vmcnt(7)
	v_lshlrev_b32_e32 v2, 16, v38
	v_and_b32_e32 v3, 0xffff0000, v38
	v_pk_fma_f32 v[0:1], v[32:33], v[0:1], v[4:5] op_sel_hi:[0,1,1]
	v_pk_mul_f32 v[0:1], v[0:1], v[2:3]
	v_lshlrev_b32_e32 v2, 16, v19
	v_and_b32_e32 v3, 0xffff0000, v19
	v_lshlrev_b32_e32 v4, 16, v39
	v_and_b32_e32 v5, 0xffff0000, v39
	v_pk_fma_f32 v[2:3], v[32:33], v[2:3], v[6:7] op_sel_hi:[0,1,1]
	v_pk_mul_f32 v[2:3], v[2:3], v[4:5]
	v_cvt_pk_bf16_f32 v0, v0, v1
	v_cvt_pk_bf16_f32 v1, v2, v3
	global_store_dwordx2 v[20:21], v[0:1], off offset:16
	ds_read2_b64 v[0:3], v26 offset0:68 offset1:70
	s_waitcnt vmcnt(7)
	v_lshlrev_b32_e32 v6, 16, v36
	v_and_b32_e32 v7, 0xffff0000, v36
	s_waitcnt lgkmcnt(0)
	v_lshlrev_b32_e32 v4, 16, v0
	v_and_b32_e32 v5, 0xffff0000, v0
	v_pk_fma_f32 v[4:5], v[32:33], v[4:5], v[8:9] op_sel_hi:[0,1,1]
	v_pk_mul_f32 v[4:5], v[4:5], v[6:7]
	v_lshlrev_b32_e32 v6, 16, v37
	v_cvt_pk_bf16_f32 v0, v4, v5
	v_lshlrev_b32_e32 v4, 16, v1
	v_and_b32_e32 v5, 0xffff0000, v1
	v_and_b32_e32 v7, 0xffff0000, v37
	v_pk_fma_f32 v[4:5], v[32:33], v[4:5], v[10:11] op_sel_hi:[0,1,1]
	v_pk_mul_f32 v[4:5], v[4:5], v[6:7]
	s_nop 0
	v_cvt_pk_bf16_f32 v1, v4, v5
	v_lshlrev_b32_e32 v4, 16, v2
	v_and_b32_e32 v5, 0xffff0000, v2
	global_store_dwordx2 v[20:21], v[0:1], off offset:32
	s_waitcnt vmcnt(7)
	v_lshlrev_b32_e32 v0, 16, v34
	v_and_b32_e32 v1, 0xffff0000, v34
	v_pk_fma_f32 v[4:5], v[32:33], v[4:5], v[12:13] op_sel_hi:[0,1,1]
	v_lshlrev_b32_e32 v2, 16, v3
	v_and_b32_e32 v3, 0xffff0000, v3
	v_pk_mul_f32 v[0:1], v[4:5], v[0:1]
	v_lshlrev_b32_e32 v4, 16, v35
	v_and_b32_e32 v5, 0xffff0000, v35
	v_pk_fma_f32 v[2:3], v[32:33], v[2:3], v[14:15] op_sel_hi:[0,1,1]
	v_pk_mul_f32 v[2:3], v[2:3], v[4:5]
	v_cvt_pk_bf16_f32 v0, v0, v1
	v_cvt_pk_bf16_f32 v1, v2, v3
	global_store_dwordx2 v[20:21], v[0:1], off offset:48
	s_barrier
	s_cbranch_scc0 .LBB0_673

; #define LAS __attribute__((address_space(3)))
; DI void hyena_unit(const Inputs& in, int l, unsigned char* ws, int half, int c, LAS unsigned char* lds, int tid) {
;     ...
;     f32x16 acc0 = {}, acc1 = {};
;     const LAS unsigned char* Zb = Zl + (size_t)b0 * ZSP * 2;
;     const int zstep = ZSP * 2;
;     ...
;     const float bias = in.hy_bias[l * 512 + c];
;     u32x2 xx[2][4];
; #pragma unroll
;     for (int k = 0; k < 2; ++k)
; #pragma unroll
;         for (int q = 0; q < 4; ++q) xx[k][q] = *(const u32x2*)(XT + (size_t)((b0 + k) * 512 + c) * L + 32 * (a0 + i32) + 8 * q + 4 * g);
.LBB0_658:
	s_or_b64 exec, exec, s[74:75]
	v_mov_b32_e32 v31, 0
	v_mov_b32_e32 v30, v31
	v_mov_b32_e32 v29, v31
	v_mov_b32_e32 v28, v31
	v_mov_b32_e32 v27, v31
	v_mov_b32_e32 v26, v31
	v_mov_b32_e32 v25, v31
	v_mov_b32_e32 v24, v31
	v_mov_b32_e32 v23, v31
	v_mov_b32_e32 v22, v31
	v_mov_b32_e32 v21, v31
	v_mov_b32_e32 v20, v31
	v_mov_b32_e32 v19, v31
	v_mov_b32_e32 v18, v31
	v_mov_b32_e32 v17, v31
	v_mov_b32_e32 v16, v31
	v_mov_b32_e32 v15, v31
	v_mov_b32_e32 v14, v31
	v_mov_b32_e32 v13, v31
	v_mov_b32_e32 v12, v31
	v_mov_b32_e32 v11, v31
	v_mov_b32_e32 v10, v31
	v_mov_b32_e32 v9, v31
	v_mov_b32_e32 v8, v31
	v_mov_b32_e32 v7, v31
	v_mov_b32_e32 v6, v31
	v_mov_b32_e32 v5, v31
	v_mov_b32_e32 v4, v31
	v_mov_b32_e32 v3, v31
	v_mov_b32_e32 v2, v31
	v_mov_b32_e32 v1, v31
	v_mov_b32_e32 v0, v31
	s_waitcnt lgkmcnt(0)
	s_barrier
	v_readlane_b32 s42, v255, 13
	s_add_i32 s74, s79, s42
	s_ashr_i32 s75, s74, 31
	s_lshl_b64 s[74:75], s[74:75], 2
	s_add_u32 s74, s60, s74
	s_addc_u32 s75, s61, s75
	global_load_dword v200, v177, s[74:75]
	v_add_u32_e32 v202, s79, v92
	v_ashrrev_i32_e32 v203, 31, v202
	v_lshlrev_b64 v[202:203], s33, v[202:203]
	v_lshlrev_b64 v[202:203], 1, v[202:203]
	v_lshl_add_u64 v[202:203], v[86:87], 0, v[202:203]
	global_load_dwordx2 v[184:185], v[202:203], off
	global_load_dwordx2 v[186:187], v[202:203], off offset:16
	global_load_dwordx2 v[188:189], v[202:203], off offset:32
	global_load_dwordx2 v[190:191], v[202:203], off offset:48
	v_add_u32_e32 v202, s79, v93
	v_ashrrev_i32_e32 v203, 31, v202
	v_lshlrev_b64 v[202:203], s33, v[202:203]
	v_lshlrev_b64 v[202:203], 1, v[202:203]
	v_lshl_add_u64 v[202:203], v[86:87], 0, v[202:203]
	global_load_dwordx2 v[192:193], v[202:203], off
	global_load_dwordx2 v[194:195], v[202:203], off offset:16
	global_load_dwordx2 v[196:197], v[202:203], off offset:32
	global_load_dwordx2 v[198:199], v[202:203], off offset:48
	s_and_saveexec_b64 vcc, s[40:41]
	s_cbranch_execz .LBB0_617
	v_mov_b32_e32 v16, 0
	s_mov_b32 s42, 0
	v_mov_b32_e32 v32, v103
	v_mov_b32_e32 v17, v16
	v_mov_b32_e32 v18, v16
	v_mov_b32_e32 v19, v16
	v_mov_b32_e32 v20, v16
	v_mov_b32_e32 v21, v16
	v_mov_b32_e32 v22, v16
	v_mov_b32_e32 v23, v16
	v_mov_b32_e32 v24, v16
	v_mov_b32_e32 v25, v16
	v_mov_b32_e32 v26, v16
	v_mov_b32_e32 v27, v16
	v_mov_b32_e32 v28, v16
	v_mov_b32_e32 v29, v16
	v_mov_b32_e32 v30, v16
	v_mov_b32_e32 v31, v16
	v_mov_b32_e32 v0, v16
	v_mov_b32_e32 v1, v16
	v_mov_b32_e32 v2, v16
	v_mov_b32_e32 v3, v16
	v_mov_b32_e32 v4, v16
	v_mov_b32_e32 v5, v16
	v_mov_b32_e32 v6, v16
	v_mov_b32_e32 v7, v16
	v_mov_b32_e32 v8, v16
	v_mov_b32_e32 v9, v16
	v_mov_b32_e32 v10, v16
	v_mov_b32_e32 v11, v16
	v_mov_b32_e32 v12, v16
	v_mov_b32_e32 v13, v16
	v_mov_b32_e32 v14, v16
	v_mov_b32_e32 v15, v16
